# v16 + early L2 writeback (buffer_wbl2 sc1) by every block on arrival at the grid barrier
# baseline (speedup 1.0000x reference)
; __device__ __forceinline__ unsigned xb_add(unsigned* p, unsigned v) { return __hip_atomic_fetch_add(p, v, __ATOMIC_RELAXED, __HIP_MEMORY_SCOPE_AGENT); }
; __device__ __forceinline__ void xcd_barrier(const XcdBarrier& b) {
;   asm volatile("s_waitcnt vmcnt(0)" ::: "memory");
;   __syncthreads();
;   if (threadIdx.x == 0) {
;     unsigned* bar = b.bar;
;     __builtin_amdgcn_s_waitcnt(0);
;     unsigned nloc = b.st[0], nx = b.st[1];
;     if (nloc == 0u) { xcd_barrier_complete(bar, b.x, nloc, nx); b.st[0] = nloc; b.st[1] = nx; }
;     const unsigned old = xb_add(&bar[XB_XSUB(b.x)], 1u);
;     const unsigned gen = old / nloc;
;     if (old + 1u == (gen + 1u) * nloc) {
.LBB0_1328:
	s_waitcnt vmcnt(0) expcnt(0) lgkmcnt(0)
	buffer_wbl2 sc1
	ds_read_b32 v2, v221
	ds_read_b32 v0, v222
	s_waitcnt lgkmcnt(1)
	v_cmp_ne_u32_e32 vcc, 0, v2
	s_cbranch_vccnz .LBB0_1343
	s_mov_b32 s10, 1
	s_branch .LBB0_1331
